# FFN-in phase start: conv tap/bias bf16 LDS copy staged with 22 loads in flight per thread (was 11 dependent round trips)
# baseline (speedup 1.0000x reference)
; #define LAS __attribute__((address_space(3)))
; __device__ __forceinline__ bf16_t f2bf(float f) { unsigned u = __float_as_uint(f); u += 0x7FFFu + ((u >> 16) & 1u); return (bf16_t)(u >> 16); }
; __device__ __forceinline__ void gemm_phase(LAS unsigned char* lds, const bf16_t* A, const bf16_t* Bt, int M, int N, int K, const Epi& E) {
;     ...
;     if (E.mode == 2) {
;         LAS bf16_t* cwl = (LAS bf16_t*)(lds + CWL_OFF);
;         for (int idx = tid; idx < 4 * DFF; idx += NTHREADS) cwl[idx] = f2bf(idx < 3 * DFF ? E.cw[idx] : E.cb[idx - 3 * DFF]);
;         asm volatile("s_waitcnt lgkmcnt(0)" ::: "memory");
;     }
.LBB0_2791:
	s_or_b64 exec, exec, s[0:1]
	v_readlane_b32 s2, v254, 51
	s_mul_i32 s1, s2, 0x8400
	s_mul_hi_u32 s0, s2, 0x8400
	s_add_u32 s6, s78, s1
	s_addc_u32 s7, s79, s0
	s_mul_i32 s1, s2, 0x2c00
	s_mul_hi_u32 s0, s2, 0x2c00
	s_add_u32 s8, s80, s1
	s_addc_u32 s9, s81, s0
	s_waitcnt lgkmcnt(0)
	v_mov_b32_e32 v2, v187
	s_movk_i32 s0, 0x2c00
	s_barrier
	s_mov_b32 s26, s69
	v_readfirstlane_b32 s14, v2
	v_cmp_gt_i32_e32 vcc, s0, v2
	s_and_saveexec_b64 s[2:3], vcc
	s_cbranch_execz .LBB0_2804
	v_readlane_b32 s0, v254, 28
	v_lshlrev_b32_e32 v0, 2, v2
	s_mov_b32 s10, s6
	s_mov_b32 s11, s7
	v_lshl_add_u32 v3, v2, 1, s0
	global_load_dword v208, v0, s[10:11]
	s_add_u32 s10, s10, 0x800
	s_addc_u32 s11, s11, 0
	global_load_dword v209, v0, s[10:11]
	s_add_u32 s10, s10, 0x800
	s_addc_u32 s11, s11, 0
	global_load_dword v210, v0, s[10:11]
	s_add_u32 s10, s10, 0x800
	s_addc_u32 s11, s11, 0
	global_load_dword v211, v0, s[10:11]
	s_add_u32 s10, s10, 0x800
	s_addc_u32 s11, s11, 0
	global_load_dword v212, v0, s[10:11]
	s_add_u32 s10, s10, 0x800
	s_addc_u32 s11, s11, 0
	global_load_dword v213, v0, s[10:11]
	s_add_u32 s10, s10, 0x800
	s_addc_u32 s11, s11, 0
	global_load_dword v214, v0, s[10:11]
	s_add_u32 s10, s10, 0x800
	s_addc_u32 s11, s11, 0
	global_load_dword v215, v0, s[10:11]
	s_add_u32 s10, s10, 0x800
	s_addc_u32 s11, s11, 0
	global_load_dword v216, v0, s[10:11]
	s_add_u32 s10, s10, 0x800
	s_addc_u32 s11, s11, 0
	global_load_dword v217, v0, s[10:11]
	s_add_u32 s10, s10, 0x800
	s_addc_u32 s11, s11, 0
	global_load_dword v218, v0, s[10:11]
	s_add_u32 s10, s10, 0x800
	s_addc_u32 s11, s11, 0
	global_load_dword v219, v0, s[10:11]
	s_add_u32 s10, s10, 0x800
	s_addc_u32 s11, s11, 0
	global_load_dword v220, v0, s[10:11]
	s_add_u32 s10, s10, 0x800
	s_addc_u32 s11, s11, 0
	global_load_dword v221, v0, s[10:11]
	s_add_u32 s10, s10, 0x800
	s_addc_u32 s11, s11, 0
	global_load_dword v222, v0, s[10:11]
	s_add_u32 s10, s10, 0x800
	s_addc_u32 s11, s11, 0
	global_load_dword v223, v0, s[10:11]
	s_add_u32 s12, s6, 0x8000
	s_addc_u32 s13, s7, 0
	s_sub_u32 s16, s8, 0x400
	s_subb_u32 s17, s9, 0
	s_cmp_lt_u32 s14, 0x100
	s_cselect_b32 s10, s12, s16
	s_cselect_b32 s11, s13, s17
	global_load_dword v224, v0, s[10:11]
	s_add_u32 s10, s8, 0x400
	s_addc_u32 s11, s9, 0
	global_load_dword v225, v0, s[10:11]
	s_add_u32 s10, s10, 0x800
	s_addc_u32 s11, s11, 0
	global_load_dword v226, v0, s[10:11]
	s_add_u32 s10, s10, 0x800
	s_addc_u32 s11, s11, 0
	global_load_dword v227, v0, s[10:11]
	s_add_u32 s10, s10, 0x800
	s_addc_u32 s11, s11, 0
	global_load_dword v228, v0, s[10:11]
	s_add_u32 s10, s10, 0x800
	s_addc_u32 s11, s11, 0
	global_load_dword v229, v0, s[10:11]
	s_movk_i32 s5, 0x7fff
	s_waitcnt vmcnt(14)
	v_bfe_u32 v230, v208, 16, 1
	v_add3_u32 v208, v208, v230, s5
	ds_write_b16_d16_hi v3, v208
	v_bfe_u32 v230, v209, 16, 1
	v_add3_u32 v209, v209, v230, s5
	ds_write_b16_d16_hi v3, v209 offset:1024
	v_bfe_u32 v230, v210, 16, 1
	v_add3_u32 v210, v210, v230, s5
	ds_write_b16_d16_hi v3, v210 offset:2048
	v_bfe_u32 v230, v211, 16, 1
	v_add3_u32 v211, v211, v230, s5
	ds_write_b16_d16_hi v3, v211 offset:3072
	v_bfe_u32 v230, v212, 16, 1
	v_add3_u32 v212, v212, v230, s5
	ds_write_b16_d16_hi v3, v212 offset:4096
	v_bfe_u32 v230, v213, 16, 1
	v_add3_u32 v213, v213, v230, s5
	ds_write_b16_d16_hi v3, v213 offset:5120
	v_bfe_u32 v230, v214, 16, 1
	v_add3_u32 v214, v214, v230, s5
	ds_write_b16_d16_hi v3, v214 offset:6144
	v_bfe_u32 v230, v215, 16, 1
	v_add3_u32 v215, v215, v230, s5
	ds_write_b16_d16_hi v3, v215 offset:7168
	s_waitcnt vmcnt(6)
	v_bfe_u32 v230, v216, 16, 1
	v_add3_u32 v216, v216, v230, s5
	ds_write_b16_d16_hi v3, v216 offset:8192
	v_bfe_u32 v230, v217, 16, 1
	v_add3_u32 v217, v217, v230, s5
	ds_write_b16_d16_hi v3, v217 offset:9216
	v_bfe_u32 v230, v218, 16, 1
	v_add3_u32 v218, v218, v230, s5
	ds_write_b16_d16_hi v3, v218 offset:10240
	v_bfe_u32 v230, v219, 16, 1
	v_add3_u32 v219, v219, v230, s5
	ds_write_b16_d16_hi v3, v219 offset:11264
	v_bfe_u32 v230, v220, 16, 1
	v_add3_u32 v220, v220, v230, s5
	ds_write_b16_d16_hi v3, v220 offset:12288
	v_bfe_u32 v230, v221, 16, 1
	v_add3_u32 v221, v221, v230, s5
	ds_write_b16_d16_hi v3, v221 offset:13312
	v_bfe_u32 v230, v222, 16, 1
	v_add3_u32 v222, v222, v230, s5
	ds_write_b16_d16_hi v3, v222 offset:14336
	v_bfe_u32 v230, v223, 16, 1
	v_add3_u32 v223, v223, v230, s5
	ds_write_b16_d16_hi v3, v223 offset:15360
	s_waitcnt vmcnt(0)
	v_bfe_u32 v230, v224, 16, 1
	v_add3_u32 v224, v224, v230, s5
	ds_write_b16_d16_hi v3, v224 offset:16384
	v_bfe_u32 v230, v225, 16, 1
	v_add3_u32 v225, v225, v230, s5
	ds_write_b16_d16_hi v3, v225 offset:17408
	v_bfe_u32 v230, v226, 16, 1
	v_add3_u32 v226, v226, v230, s5
	ds_write_b16_d16_hi v3, v226 offset:18432
	v_bfe_u32 v230, v227, 16, 1
	v_add3_u32 v227, v227, v230, s5
	ds_write_b16_d16_hi v3, v227 offset:19456
	v_bfe_u32 v230, v228, 16, 1
	v_add3_u32 v228, v228, v230, s5
	ds_write_b16_d16_hi v3, v228 offset:20480
	v_bfe_u32 v230, v229, 16, 1
	v_add3_u32 v229, v229, v230, s5
	ds_write_b16_d16_hi v3, v229 offset:21504
